# combined: v_fmac recurrence, in-place attention accumulators (no per-tile copies), single wait in the S5 pass-2 preheader, on top of the permlane attention exchange
# baseline (speedup 1.0000x reference)
.LBB0_173:
	s_or_b64 exec, exec, s[2:3]
	v_mov_b32_e32 v72, 0
	v_mov_b32_e32 v76, 0
	v_mov_b32_e32 v77, 0
	v_mov_b32_e32 v78, 0
	v_mov_b32_e32 v79, 0
	s_and_saveexec_b64 s[2:3], s[0:1]
	s_cbranch_execz .LBB0_175
	global_load_dwordx4 v[76:79], v[0:1], off offset:64

.LBB0_177:
	s_or_b64 exec, exec, s[2:3]
	v_mov_b32_e32 v80, 0
	v_mov_b32_e32 v84, 0
	v_mov_b32_e32 v85, 0
	v_mov_b32_e32 v86, 0
	v_mov_b32_e32 v87, 0
	s_and_saveexec_b64 s[2:3], s[0:1]
	s_cbranch_execz .LBB0_179
	global_load_dwordx4 v[84:87], v[0:1], off offset:2048

.LBB0_181:
	s_or_b64 exec, exec, s[2:3]
	v_mov_b32_e32 v88, 0
	v_mov_b32_e32 v92, 0
	v_mov_b32_e32 v93, 0
	v_mov_b32_e32 v94, 0
	v_mov_b32_e32 v95, 0
	s_and_saveexec_b64 s[2:3], s[0:1]
	s_cbranch_execz .LBB0_183
	global_load_dwordx4 v[92:95], v[0:1], off offset:2112

.LBB0_185:
	s_or_b64 exec, exec, s[2:3]
	s_lshl_b32 s24, s14, 2
	v_lshl_add_u64 v[0:1], v[160:161], 0, s[24:25]
	global_load_dwordx4 v[96:99], v[0:1], off
	global_load_dwordx4 v[100:103], v[0:1], off offset:32
	s_lshl_b32 s2, s66, 7
	s_and_b32 s2, s2, 0xffffe000
	v_or3_b32 v120, s2, v197, v155
	v_ashrrev_i32_e32 v121, 31, v120
	v_lshl_add_u64 v[0:1], v[168:169], 0, v[120:121]
	v_lshl_add_u64 v[2:3], v[166:167], 0, v[120:121]
	v_lshl_add_u64 v[4:5], v[164:165], 0, v[120:121]
	v_lshl_add_u64 v[6:7], v[162:163], 0, v[120:121]
	v_cndmask_b32_e64 v1, v1, 0, s[10:11]
	v_cndmask_b32_e64 v0, v0, v154, s[10:11]
	v_cndmask_b32_e64 v3, v3, 0, s[8:9]
	v_cndmask_b32_e64 v2, v2, v154, s[8:9]
	v_cndmask_b32_e64 v5, v5, 0, s[6:7]
	v_cndmask_b32_e64 v4, v4, v154, s[6:7]
	v_cndmask_b32_e64 v7, v7, 0, s[4:5]
	v_cndmask_b32_e64 v6, v6, v154, s[4:5]
	v_lshlrev_b64 v[0:1], 11, v[0:1]
	v_mov_b32_e32 v185, v149
	v_lshlrev_b64 v[2:3], 11, v[2:3]
	v_lshlrev_b64 v[4:5], 11, v[4:5]
	v_lshlrev_b64 v[6:7], 11, v[6:7]
	v_lshl_add_u64 v[0:1], s[84:85], 0, v[0:1]
	v_lshl_add_u64 v[2:3], s[84:85], 0, v[2:3]
	v_lshl_add_u64 v[4:5], s[84:85], 0, v[4:5]
	v_lshl_add_u64 v[6:7], s[84:85], 0, v[6:7]
	v_lshl_add_u64 v[0:1], v[0:1], 0, v[184:185]
	v_lshl_add_u64 v[2:3], v[2:3], 0, v[184:185]
	v_lshl_add_u64 v[4:5], v[4:5], 0, v[184:185]
	v_lshl_add_u64 v[6:7], v[6:7], 0, v[184:185]
	s_lshl_b32 s24, s14, 1
	s_cmp_lt_u32 s66, 64
	s_cselect_b64 s[2:3], -1, 0
	v_lshl_add_u64 v[126:127], v[170:171], 0, s[24:25]
	v_lshl_add_u64 v[184:185], s[84:85], 0, v[184:185]
	s_and_b64 s[50:51], s[2:3], s[12:13]
	s_mov_b32 s24, s28
	global_load_dwordx4 v[112:115], v[0:1], off
	global_load_dwordx4 v[116:119], v[2:3], off
	global_load_dwordx4 v[104:107], v[4:5], off
	global_load_dwordx4 v[108:111], v[6:7], off
	v_add_u32_e32 v0, s15, v205
	v_ashrrev_i32_e32 v1, 31, v0
	v_lshl_add_u64 v[122:123], s[42:43], 0, v[0:1]
	v_lshl_add_u64 v[124:125], s[44:45], 0, v[0:1]
	v_mov_b32_e32 v186, v48
	v_mov_b32_e32 v187, v50
	v_mov_b32_e32 v188, v49
	v_mov_b32_e32 v189, v51
	v_xor_b32_e32 v241, 0x80000000, v173
	v_xor_b32_e32 v242, 0x80000000, v175
	v_mov_b32_e32 v240, 0xbdd2d3e7
	s_waitcnt vmcnt(0)
	s_branch .LBB0_188

.LBB0_648:
	v_mov_b32_e32 v139, v0
	s_waitcnt lgkmcnt(0)
	v_lshl_add_u64 v[216:217], v[138:139], 1, v[156:157]
	s_nop 7
	v_cvt_pk_bf16_f32 v4, v32, v33
	v_cvt_pk_bf16_f32 v5, v34, v35
	v_cvt_pk_bf16_f32 v6, v36, v37
	v_cvt_pk_bf16_f32 v7, v38, v39
	v_cvt_pk_bf16_f32 v8, v40, v41
	v_cvt_pk_bf16_f32 v9, v42, v43
	v_cvt_pk_bf16_f32 v10, v44, v45
	v_cvt_pk_bf16_f32 v11, v46, v47
	v_cvt_pk_bf16_f32 v12, v16, v17
	v_cvt_pk_bf16_f32 v13, v18, v19
	v_cvt_pk_bf16_f32 v14, v20, v21
	v_cvt_pk_bf16_f32 v15, v22, v23
	v_cvt_pk_bf16_f32 v218, v24, v25
	v_cvt_pk_bf16_f32 v219, v26, v27
	v_cvt_pk_bf16_f32 v220, v28, v29
	v_cvt_pk_bf16_f32 v221, v30, v31
	s_nop 1
	v_permlane32_swap_b32_e32 v4, v6
	v_permlane32_swap_b32_e32 v5, v7
	v_permlane32_swap_b32_e32 v8, v10
	v_permlane32_swap_b32_e32 v9, v11
	v_permlane32_swap_b32_e32 v12, v14
	v_permlane32_swap_b32_e32 v13, v15
	v_permlane32_swap_b32_e32 v218, v220
	v_permlane32_swap_b32_e32 v219, v221
	global_store_dwordx4 v[216:217], v[4:7], off
	global_store_dwordx4 v[216:217], v[8:11], off offset:32
	global_store_dwordx4 v[216:217], v[12:15], off offset:64
	global_store_dwordx4 v[216:217], v[218:221], off offset:96
	s_add_i32 s20, s20, s72
	s_cmpk_lt_i32 s20, 0x4000
	s_cbranch_scc0 .LBB0_656

.LBB0_650:
	s_and_b64 vcc, exec, s[18:19]
	v_mov_b32_e32 v139, v14
	s_cbranch_vccnz .LBB0_648
.LBB0_651:
	s_max_i32 s0, s14, 0
	s_mov_b32 s6, s14
	s_add_i32 s14, s0, -1
	s_lshl_b32 s0, s14, 5
	s_add_i32 s0, s23, s0
	s_cmp_gt_i32 s6, 0
	s_waitcnt vmcnt(0)
	s_cselect_b32 s0, s0, 0x8002
	s_waitcnt lgkmcnt(0)
	v_or_b32_e32 v2, s0, v135
	v_ashrrev_i32_e32 v3, 31, v2
	v_lshlrev_b64 v[2:3], 11, v[2:3]
	ds_write_b128 v167, v[108:111]
	ds_write_b128 v167, v[104:107] offset:144
	ds_write_b128 v167, v[100:103] offset:288
	ds_write_b128 v167, v[96:99] offset:432
	ds_write_b128 v168, v[92:95] offset:4608
	ds_write_b128 v168, v[88:91] offset:4800
	ds_write_b128 v168, v[84:87] offset:4992
	ds_write_b128 v168, v[80:83] offset:5184
	v_lshl_or_b32 v2, v158, 1, v2
	v_lshl_add_u64 v[4:5], s[24:25], 0, v[2:3]
	v_lshl_add_u64 v[2:3], s[26:27], 0, v[2:3]
	global_load_dwordx4 v[108:111], v[4:5], off offset:-4096
	global_load_dwordx4 v[104:107], v[4:5], off offset:-2048
	global_load_dwordx4 v[100:103], v[4:5], off
	global_load_dwordx4 v[96:99], v[4:5], off offset:2048
	global_load_dwordx4 v[92:95], v[2:3], off offset:-4096
	global_load_dwordx4 v[88:91], v[2:3], off offset:-2048
	global_load_dwordx4 v[84:87], v[2:3], off
	global_load_dwordx4 v[80:83], v[2:3], off offset:2048
	ds_read_b128 v[128:131], v169
	ds_read_b128 v[10:13], v169 offset:32
	ds_read_b128 v[6:9], v169 offset:64
	ds_read_b128 v[2:5], v169 offset:96
	s_cmp_lt_i32 s6, 0
	s_cselect_b64 s[0:1], -1, 0
	s_cmp_gt_i32 s6, -1
	s_cselect_b64 s[2:3], -1, 0
	s_cmp_lg_u32 s6, s22
	s_cselect_b64 s[6:7], -1, 0
	s_and_b64 s[6:7], s[2:3], s[6:7]
	s_mov_b64 s[18:19], -1
	s_and_b64 vcc, exec, s[6:7]
	v_mbcnt_hi_u32_b32 v1, -1, v195
	s_mov_b64 s[6:7], -1
	s_cbranch_vccz .LBB0_653
	s_waitcnt lgkmcnt(3)
	v_mfma_f32_32x32x16_bf16 v[48:63], v[128:131], v[112:115], 0
	s_mov_b64 s[6:7], 0
	s_waitcnt lgkmcnt(2)
	v_mfma_f32_32x32x16_bf16 v[48:63], v[10:13], v[116:119], v[48:63]
	s_waitcnt lgkmcnt(1)
	v_mfma_f32_32x32x16_bf16 v[48:63], v[6:9], v[120:123], v[48:63]
	s_waitcnt lgkmcnt(0)
	v_mfma_f32_32x32x16_bf16 v[48:63], v[2:5], v[124:127], v[48:63]
	s_nop 11
	v_exp_f32_e32 v14, v48
	v_exp_f32_e32 v15, v49
	v_exp_f32_e32 v48, v50
	v_exp_f32_e32 v49, v51
	v_exp_f32_e32 v50, v52
	v_exp_f32_e32 v51, v53
	v_exp_f32_e32 v52, v54
	v_exp_f32_e32 v53, v55
	v_exp_f32_e32 v54, v56
	v_exp_f32_e32 v55, v57
	v_exp_f32_e32 v56, v58
	v_exp_f32_e32 v57, v59
	v_exp_f32_e32 v58, v60
	v_exp_f32_e32 v59, v61
	v_exp_f32_e32 v60, v62
	v_exp_f32_e32 v61, v63
	v_pk_add_f32 v[14:15], v[14:15], 1.0 op_sel_hi:[1,0]
	v_pk_add_f32 v[48:49], v[48:49], 1.0 op_sel_hi:[1,0]
	v_pk_add_f32 v[58:59], v[58:59], 1.0 op_sel_hi:[1,0]
	v_pk_add_f32 v[50:51], v[50:51], 1.0 op_sel_hi:[1,0]
	v_pk_add_f32 v[52:53], v[52:53], 1.0 op_sel_hi:[1,0]
	v_rcp_f32_e32 v14, v14
	v_rcp_f32_e32 v15, v15
	v_rcp_f32_e32 v48, v48
	v_rcp_f32_e32 v49, v49
	v_rcp_f32_e32 v192, v58
	v_rcp_f32_e32 v193, v59
	v_pk_add_f32 v[58:59], v[60:61], 1.0 op_sel_hi:[1,0]
	v_pk_add_f32 v[54:55], v[54:55], 1.0 op_sel_hi:[1,0]
	v_pk_add_f32 v[56:57], v[56:57], 1.0 op_sel_hi:[1,0]
	v_rcp_f32_e32 v50, v50
	v_rcp_f32_e32 v51, v51
	v_rcp_f32_e32 v52, v52
	v_rcp_f32_e32 v53, v53
	v_rcp_f32_e32 v205, v59
	v_rcp_f32_e32 v68, v54
	v_rcp_f32_e32 v69, v55
	v_rcp_f32_e32 v70, v56
	v_rcp_f32_e32 v71, v57
	v_rcp_f32_e32 v204, v58
	v_pk_add_f32 v[54:55], v[14:15], 1.0 op_sel_hi:[1,0] neg_lo:[1,0] neg_hi:[1,0]
	v_pk_add_f32 v[56:57], v[48:49], 1.0 op_sel_hi:[1,0] neg_lo:[1,0] neg_hi:[1,0]
	v_pk_add_f32 v[62:63], v[50:51], 1.0 op_sel_hi:[1,0] neg_lo:[1,0] neg_hi:[1,0]
	v_pk_add_f32 v[64:65], v[52:53], 1.0 op_sel_hi:[1,0] neg_lo:[1,0] neg_hi:[1,0]
	v_pk_mul_f32 v[58:59], v[54:55], v[56:57]
	v_pk_add_f32 v[72:73], v[68:69], 1.0 op_sel_hi:[1,0] neg_lo:[1,0] neg_hi:[1,0]
	v_pk_add_f32 v[74:75], v[70:71], 1.0 op_sel_hi:[1,0] neg_lo:[1,0] neg_hi:[1,0]
	v_mul_f32_e32 v214, v58, v59
	v_pk_mul_f32 v[58:59], v[62:63], v[64:65]
	v_pk_add_f32 v[206:207], v[192:193], 1.0 op_sel_hi:[1,0] neg_lo:[1,0] neg_hi:[1,0]
	v_pk_add_f32 v[76:77], v[204:205], 1.0 op_sel_hi:[1,0] neg_lo:[1,0] neg_hi:[1,0]
	v_mul_f32_e32 v54, v58, v59
	v_pk_mul_f32 v[58:59], v[72:73], v[74:75]
	v_mov_b32_e32 v67, v54
	v_mul_f32_e32 v62, v58, v59
	v_pk_mul_f32 v[58:59], v[206:207], v[76:77]
	v_mov_b32_e32 v61, v62
	v_mul_f32_e32 v58, v58, v59
	v_mov_b32_e32 v59, v58
	v_mov_b32_e32 v215, v214
	v_permlane32_swap_b32_e32 v67, v54
	v_permlane32_swap_b32_e32 v61, v62
	v_permlane32_swap_b32_e32 v58, v59
	v_permlane32_swap_b32_e32 v214, v215
	s_nop 1
	v_mul_f32_e32 v58, v58, v59
	v_mul_f32_e32 v62, v62, v58
	v_mul_f32_e32 v61, v61, v62
	v_mul_f32_e32 v54, v54, v61
	v_mov_b32_e32 v60, v215
	v_mul_f32_e32 v66, v67, v54
	v_mul_f32_e32 v206, v60, v66
	v_cndmask_b32_e64 v60, v66, v206, s[4:5]
	v_cndmask_b32_e64 v72, 1.0, v59, s[4:5]
	v_mul_f32_e32 v59, v139, v60
	v_cndmask_b32_e64 v54, v61, v54, s[4:5]
	v_cndmask_b32_e64 v61, v58, v62, s[4:5]
	v_mul_f32_e32 v58, v57, v59
	v_mul_f32_e32 v57, v56, v58
	v_mul_f32_e32 v56, v55, v57
	v_mul_f32_e32 v55, v139, v54
	v_mul_f32_e32 v54, v65, v55
	v_pk_mul_f32 v[14:15], v[14:15], v[56:57]
	v_mul_f32_e32 v57, v64, v54
	v_mul_f32_e32 v79, v139, v61
	v_mul_f32_e32 v56, v63, v57
	v_mul_f32_e32 v78, v75, v79
	v_pk_mul_f32 v[48:49], v[48:49], v[58:59]
	v_pk_mul_f32 v[50:51], v[50:51], v[56:57]
	v_pk_mul_f32 v[52:53], v[52:53], v[54:55]
	v_cvt_pk_bf16_f32 v200, v14, v15
	v_mul_f32_e32 v15, v74, v78
	v_mul_f32_e32 v211, v139, v72
	ds_read_b64_tr_b16 v[64:65], v141
	ds_read_b64_tr_b16 v[66:67], v141 offset:1536
	ds_read_b64_tr_b16 v[188:189], v141 offset:3072
	ds_read_b64_tr_b16 v[190:191], v141 offset:4608
	ds_read_b64_tr_b16 v[196:197], v141 offset:64
	ds_read_b64_tr_b16 v[198:199], v141 offset:1600
	ds_read_b64_tr_b16 v[184:185], v141 offset:3136
	ds_read_b64_tr_b16 v[186:187], v141 offset:4672
	s_waitcnt lgkmcnt(0)
	v_cvt_pk_bf16_f32 v201, v48, v49
	v_cvt_pk_bf16_f32 v202, v50, v51
	v_cvt_pk_bf16_f32 v203, v52, v53
	v_mul_f32_e32 v14, v73, v15
	v_mul_f32_e32 v210, v211, v77
	v_mfma_f32_32x32x16_bf16 v[32:47], v[64:67], v[200:203], v[32:47]
	v_mul_f32_e64 v14, v68, v14
	v_mul_f32_e64 v15, v69, v15
	v_mul_f32_e64 v208, v70, v78
	v_mul_f32_e64 v209, v71, v79
	v_mul_f32_e32 v213, v76, v210
	v_mul_f32_e32 v212, v207, v213
	v_pk_mul_f32 v[192:193], v[192:193], v[212:213]
	v_mfma_f32_32x32x16_bf16 v[16:31], v[196:199], v[200:203], v[16:31]
	v_cvt_pk_bf16_f32 v196, v14, v15
	v_mov_b32_e32 v14, v214
	v_mul_f32_e32 v14, v14, v206
	v_mul_f32_e32 v14, v139, v14
	v_mul_f32_e64 v200, v204, v210
	v_mul_f32_e64 v201, v205, v211
	v_cmp_gt_f32_e32 vcc, s21, v14
	v_cvt_pk_bf16_f32 v197, v208, v209
	v_cvt_pk_bf16_f32 v198, v192, v193
	v_cvt_pk_bf16_f32 v199, v200, v201
	s_cmp_eq_u64 vcc, exec
	s_cselect_b64 s[18:19], -1, 0
	v_mfma_f32_32x32x16_bf16 v[32:47], v[188:191], v[196:199], v[32:47]
	v_mfma_f32_32x32x16_bf16 v[16:31], v[184:187], v[196:199], v[16:31]
.LBB0_653:
	s_andn2_b64 vcc, exec, s[6:7]
	s_cbranch_vccnz .LBB0_650
	s_waitcnt lgkmcnt(3)
	v_mfma_f32_32x32x16_bf16 v[48:63], v[128:131], v[112:115], 0
	s_nop 7
	v_cndmask_b32_e64 v68, v133, 16, s[0:1]
	v_cmp_lt_u32_e32 vcc, v132, v68
	v_cmp_lt_u32_e64 s[10:11], v143, v68
	v_cmp_lt_u32_e64 s[0:1], v145, v68
	s_or_b64 vcc, s[10:11], vcc
	v_cmp_lt_u32_e64 s[6:7], v149, v68
	s_waitcnt lgkmcnt(2)
	v_mfma_f32_32x32x16_bf16 v[48:63], v[10:13], v[116:119], v[48:63]
	s_waitcnt lgkmcnt(1)
	v_mfma_f32_32x32x16_bf16 v[48:63], v[6:9], v[120:123], v[48:63]
	s_waitcnt lgkmcnt(0)
	v_mfma_f32_32x32x16_bf16 v[48:63], v[2:5], v[124:127], v[48:63]
	s_nop 11
	v_exp_f32_e32 v2, v48
	v_exp_f32_e32 v3, v49
	v_exp_f32_e32 v4, v50
	v_exp_f32_e32 v5, v51
	v_exp_f32_e32 v6, v52
	v_exp_f32_e32 v7, v53
	v_pk_add_f32 v[2:3], v[2:3], 1.0 op_sel_hi:[1,0]
	v_exp_f32_e32 v8, v54
	v_exp_f32_e32 v9, v55
	v_pk_add_f32 v[4:5], v[4:5], 1.0 op_sel_hi:[1,0]
	v_rcp_f32_e32 v2, v2
	v_rcp_f32_e32 v3, v3
	v_rcp_f32_e32 v4, v4
	v_rcp_f32_e32 v5, v5
	v_pk_add_f32 v[6:7], v[6:7], 1.0 op_sel_hi:[1,0]
	v_exp_f32_e32 v50, v56
	v_exp_f32_e32 v51, v57
	v_rcp_f32_e32 v6, v6
	v_rcp_f32_e32 v7, v7
	v_pk_add_f32 v[8:9], v[8:9], 1.0 op_sel_hi:[1,0]
	v_pk_add_f32 v[10:11], v[2:3], 1.0 op_sel_hi:[1,0] neg_lo:[1,0] neg_hi:[1,0]
	v_rcp_f32_e32 v8, v8
	v_pk_add_f32 v[12:13], v[4:5], 1.0 op_sel_hi:[1,0] neg_lo:[1,0] neg_hi:[1,0]
	v_cndmask_b32_e64 v11, 1.0, v11, s[10:11]
	v_cndmask_b32_e64 v49, 0, v3, s[10:11]
	v_cmp_lt_u32_e64 s[10:11], v147, v68
	v_rcp_f32_e32 v9, v9
	v_exp_f32_e32 v54, v58
	v_exp_f32_e32 v55, v59
	v_cndmask_b32_e64 v13, 1.0, v13, s[10:11]
	s_or_b64 s[0:1], s[10:11], s[0:1]
	v_cndmask_b32_e64 v5, 0, v5, s[10:11]
	v_cmp_lt_u32_e64 s[10:11], v151, v68
	v_pk_add_f32 v[50:51], v[50:51], 1.0 op_sel_hi:[1,0]
	v_pk_add_f32 v[14:15], v[6:7], 1.0 op_sel_hi:[1,0] neg_lo:[1,0] neg_hi:[1,0]
	v_cndmask_b32_e32 v10, 1.0, v10, vcc
	v_cndmask_b32_e32 v48, 0, v2, vcc
	s_or_b64 vcc, s[10:11], s[6:7]
	v_rcp_f32_e32 v50, v50
	v_rcp_f32_e32 v51, v51
	v_cndmask_b32_e64 v12, 1.0, v12, s[0:1]
	v_cndmask_b32_e64 v4, 0, v4, s[0:1]
	v_cndmask_b32_e32 v14, 1.0, v14, vcc
	v_cndmask_b32_e32 v6, 0, v6, vcc
	v_cmp_lt_u32_e32 vcc, v153, v68
	v_cmp_lt_u32_e64 s[0:1], v155, v68
	v_pk_add_f32 v[2:3], v[8:9], 1.0 op_sel_hi:[1,0] neg_lo:[1,0] neg_hi:[1,0]
	s_or_b64 vcc, s[0:1], vcc
	v_pk_add_f32 v[54:55], v[54:55], 1.0 op_sel_hi:[1,0]
	v_cndmask_b32_e64 v53, 1.0, v3, s[0:1]
	v_cndmask_b32_e32 v52, 1.0, v2, vcc
	v_cndmask_b32_e32 v8, 0, v8, vcc
	v_cndmask_b32_e64 v9, 0, v9, s[0:1]
	v_cmp_lt_u32_e32 vcc, v159, v68
	v_cmp_lt_u32_e64 s[0:1], v160, v68
	v_rcp_f32_e32 v54, v54
	v_rcp_f32_e32 v55, v55
	v_pk_add_f32 v[2:3], v[50:51], 1.0 op_sel_hi:[1,0] neg_lo:[1,0] neg_hi:[1,0]
	s_or_b64 vcc, s[0:1], vcc
	v_cndmask_b32_e64 v57, 1.0, v3, s[0:1]
	v_cndmask_b32_e32 v56, 1.0, v2, vcc
	v_cndmask_b32_e32 v58, 0, v50, vcc
	v_cndmask_b32_e64 v59, 0, v51, s[0:1]
	v_cmp_lt_u32_e32 vcc, v161, v68
	v_cmp_lt_u32_e64 s[0:1], v162, v68
	v_exp_f32_e32 v50, v60
	v_exp_f32_e32 v51, v61
	s_or_b64 vcc, s[0:1], vcc
	v_pk_add_f32 v[2:3], v[54:55], 1.0 op_sel_hi:[1,0] neg_lo:[1,0] neg_hi:[1,0]
	v_cndmask_b32_e32 v64, 0, v54, vcc
	v_cndmask_b32_e64 v65, 0, v55, s[0:1]
	v_exp_f32_e32 v54, v62
	v_exp_f32_e32 v55, v63
	v_pk_add_f32 v[50:51], v[50:51], 1.0 op_sel_hi:[1,0]
	v_cndmask_b32_e64 v61, 1.0, v3, s[0:1]
	v_rcp_f32_e32 v50, v50
	v_rcp_f32_e32 v51, v51
	v_pk_add_f32 v[54:55], v[54:55], 1.0 op_sel_hi:[1,0]
	v_cndmask_b32_e32 v60, 1.0, v2, vcc
	v_rcp_f32_e32 v54, v54
	v_rcp_f32_e32 v55, v55
	v_cmp_lt_u32_e32 vcc, v163, v68
	v_cmp_lt_u32_e64 s[0:1], v164, v68
	v_pk_add_f32 v[2:3], v[50:51], 1.0 op_sel_hi:[1,0] neg_lo:[1,0] neg_hi:[1,0]
	s_or_b64 vcc, s[0:1], vcc
	v_cndmask_b32_e64 v63, 1.0, v3, s[0:1]
	v_cndmask_b32_e32 v62, 1.0, v2, vcc
	v_cndmask_b32_e32 v66, 0, v50, vcc
	v_cndmask_b32_e64 v67, 0, v51, s[0:1]
	v_pk_add_f32 v[2:3], v[54:55], 1.0 op_sel_hi:[1,0] neg_lo:[1,0] neg_hi:[1,0]
	v_cmp_lt_u32_e32 vcc, v165, v68
	v_cmp_lt_u32_e64 s[0:1], v166, v68
	s_or_b64 vcc, s[0:1], vcc
	v_cndmask_b32_e32 v68, 1.0, v2, vcc
	v_cndmask_b32_e64 v69, 1.0, v3, s[0:1]
	v_cndmask_b32_e64 v15, 1.0, v15, s[10:11]
	v_cndmask_b32_e32 v70, 0, v54, vcc
	v_pk_mul_f32 v[50:51], v[14:15], v[52:53]
	v_cndmask_b32_e64 v71, 0, v55, s[0:1]
	v_pk_mul_f32 v[2:3], v[10:11], v[12:13]
	s_nop 0
	v_mul_f32_e32 v1, v2, v3
	v_mul_f32_e32 v3, v50, v51
	v_pk_mul_f32 v[50:51], v[56:57], v[60:61]
	v_mov_b32_e32 v56, v3
	v_mul_f32_e32 v14, v50, v51
	v_pk_mul_f32 v[50:51], v[62:63], v[68:69]
	v_mov_b32_e32 v10, v14
	v_mul_f32_e32 v50, v50, v51
	v_mov_b32_e32 v51, v50
	v_mov_b32_e32 v2, v1
	v_permlane32_swap_b32_e32 v56, v3
	v_permlane32_swap_b32_e32 v10, v14
	v_permlane32_swap_b32_e32 v50, v51
	v_permlane32_swap_b32_e32 v1, v2
	s_nop 1
	v_mul_f32_e32 v50, v50, v51
	v_mul_f32_e32 v14, v14, v50
	v_mul_f32_e32 v10, v10, v14
	v_mul_f32_e32 v55, v3, v10
	v_mov_b32_e32 v54, v2
	v_mul_f32_e32 v56, v56, v55
	v_mul_f32_e32 v3, v54, v56
	v_cndmask_b32_e64 v54, v56, v3, s[4:5]
	v_cndmask_b32_e64 v56, 1.0, v51, s[4:5]
	v_mul_f32_e32 v51, v139, v54
	v_cndmask_b32_e64 v10, v10, v55, s[4:5]
	v_cndmask_b32_e64 v14, v50, v14, s[4:5]
	v_mul_f32_e32 v50, v13, v51
	v_pk_mul_f32 v[72:73], v[4:5], v[50:51]
	v_mul_f32_e32 v5, v139, v10
	v_mul_f32_e32 v13, v12, v50
	v_mul_f32_e32 v4, v53, v5
	v_mul_f32_e32 v12, v11, v13
	v_mul_f32_e32 v11, v52, v4
	v_cndmask_b32_e64 v7, 0, v7, s[10:11]
	v_mul_f32_e32 v10, v15, v11
	v_pk_mul_f32 v[54:55], v[48:49], v[12:13]
	v_pk_mul_f32 v[74:75], v[6:7], v[10:11]
	v_pk_mul_f32 v[76:77], v[8:9], v[4:5]
	v_cvt_pk_bf16_f32 v52, v54, v55
	v_cvt_pk_bf16_f32 v53, v72, v73
	v_cvt_pk_bf16_f32 v54, v74, v75
	v_cvt_pk_bf16_f32 v55, v76, v77
	v_mul_f32_e32 v79, v139, v14
	ds_read_b64_tr_b16 v[48:49], v141
	ds_read_b64_tr_b16 v[50:51], v141 offset:1536
	ds_read_b64_tr_b16 v[8:9], v141 offset:3072
	ds_read_b64_tr_b16 v[10:11], v141 offset:4608
	ds_read_b64_tr_b16 v[12:13], v141 offset:64
	ds_read_b64_tr_b16 v[14:15], v141 offset:1600
	ds_read_b64_tr_b16 v[4:5], v141 offset:3136
	ds_read_b64_tr_b16 v[6:7], v141 offset:4672
	s_waitcnt lgkmcnt(0)
	v_mul_f32_e32 v78, v61, v79
	v_mfma_f32_32x32x16_bf16 v[32:47], v[48:51], v[52:55], v[32:47]
	v_mul_f32_e32 v61, v60, v78
	v_mul_f32_e32 v60, v57, v61
	v_mul_f32_e32 v57, v139, v56
	v_mul_f32_e32 v56, v57, v69
	v_mul_f32_e64 v48, v58, v60
	v_mul_f32_e64 v49, v59, v61
	v_mul_f32_e32 v59, v68, v56
	v_mul_f32_e32 v58, v63, v59
	v_mfma_f32_32x32x16_bf16 v[16:31], v[12:15], v[52:55], v[16:31]
	v_mul_f32_e64 v50, v64, v78
	v_mul_f32_e64 v51, v65, v79
	v_mul_f32_e64 v14, v66, v58
	v_mul_f32_e64 v15, v67, v59
	v_mul_f32_e64 v52, v70, v56
	v_mul_f32_e64 v53, v71, v57
	v_cvt_pk_bf16_f32 v12, v48, v49
	v_cvt_pk_bf16_f32 v13, v50, v51
	v_cvt_pk_bf16_f32 v14, v14, v15
	v_cvt_pk_bf16_f32 v15, v52, v53
	s_nop 1
	v_mfma_f32_32x32x16_bf16 v[32:47], v[8:11], v[12:15], v[32:47]
	s_and_b64 vcc, exec, s[2:3]
	v_mfma_f32_32x32x16_bf16 v[16:31], v[4:7], v[12:15], v[16:31]
	s_cbranch_vccz .LBB0_650
	v_mul_f32_e32 v1, v1, v3
	v_mul_f32_e32 v14, v139, v1
	v_cmp_gt_f32_e32 vcc, s21, v14
	s_cmp_eq_u64 vcc, exec
	s_cselect_b64 s[18:19], -1, 0
	s_branch .LBB0_650
